# P4 latent-norm loop: all 8 tokens' loads issued up front (24 loads in flight), counted vmcnt
# baseline (speedup 1.0000x reference)
; __device__ __forceinline__ unsigned pk2(float lo, float hi) { f32x2_t v = {lo, hi}; bf16x2_t b = __builtin_convertvector(v, bf16x2_t); return __builtin_bit_cast(unsigned, b); }
; __global__ void __launch_bounds__(512, 2) mega_fwd(Args args) {
;     ...
;         for (int m = gw; m < T; m += NGW) {
;             const bf16_t* zr = Z + (size_t)m * ZLD;
;             {
;                 const int h_ = lane >> 4, pc = lane & 15, fr_ = m & 15, fw_ = (m >> 4) & 3, ch_ = (m >> 6) & 31, b_ = m >> 11;
;                 const u32x4 gqv = *(const u32x4*)(zr + ZGQ + h_ * 128 + pc * 8);
;                 *(u32x4*)(H + ((((size_t)((b_ * 4 + h_) * 32 + ch_) * 4 + fw_) * 4 + (pc >> 2)) * 64 + (pc & 3) * 16 + fr_) * 8) = gqv;
;             }
;             {
;                 const u32x4 u = *(const u32x4*)(zr + ZQ + lane * 8);
;                 float v[8] = {bflo(u.x), bfhi(u.x), bflo(u.y), bfhi(u.y), bflo(u.z), bfhi(u.z), bflo(u.w), bfhi(u.w)};
;                 float sq = 0.f;
; #pragma unroll
;                 for (int e = 0; e < 8; ++e) sq += v[e] * v[e];
;                 const float r = rsqrtf(wave_sum(sq) * (1.f / 512.f) + EPS);
;                 const f32x4 g0 = *(const f32x4*)(args.in[9] + lane * 8), g1 = *(const f32x4*)(args.in[9] + lane * 8 + 4);
;                 u32x4 w; w.x = pk2(v[0] * r * g0.x, v[1] * r * g0.y); w.y = pk2(v[2] * r * g0.z, v[3] * r * g0.w); w.z = pk2(v[4] * r * g1.x, v[5] * r * g1.y); w.w = pk2(v[6] * r * g1.z, v[7] * r * g1.w);
;                 *(u32x4*)(QA + (size_t)m * 512 + lane * 8) = w;
;             }
;             {
;                 const u32x2 u = *(const u32x2*)(zr + ZKV + lane * 4);
;                 const float v0 = bflo(u.x), v1 = bfhi(u.x), v2 = bflo(u.y), v3 = bfhi(u.y);
;                 const float r = rsqrtf(wave_sum(v0 * v0 + v1 * v1 + v2 * v2 + v3 * v3) * (1.f / 256.f) + EPS);
;                 const f32x4 g0 = *(const f32x4*)(args.in[11] + lane * 4);
;                 u32x2 w; w.x = pk2(v0 * r * g0.x, v1 * r * g0.y); w.y = pk2(v2 * r * g0.z, v3 * r * g0.w);
;                 *(u32x2*)(KVA + (size_t)m * 256 + lane * 4) = w;
;             }
;         }
.LBB0_600:
	v_readlane_b32 s0, v238, 38
	s_cmpk_gt_i32 s0, 0x3fff
	v_readlane_b32 s1, v238, 39
	s_cbranch_scc1 .LBB0_603
	v_readlane_b32 s60, v238, 5
	v_readlane_b32 s62, v238, 7
	v_readlane_b32 s63, v238, 8
	v_mov_b32_e32 v17, 0
	v_lshlrev_b32_e32 v16, 5, v184
	v_readlane_b32 s66, v238, 11
	v_readlane_b32 s67, v238, 12
	v_readlane_b32 s70, v238, 15
	v_readlane_b32 s71, v238, 16
	s_mov_b64 s[2:3], s[62:63]
	v_readlane_b32 s0, v238, 38
	s_mov_b64 s[6:7], s[66:67]
	s_mov_b64 s[10:11], s[70:71]
	v_lshl_add_u64 v[4:5], s[2:3], 0, v[16:17]
	v_lshlrev_b32_e32 v16, 4, v184
	s_mov_b32 s12, s0
	v_and_b32_e32 v3, 15, v185
	v_lshlrev_b32_e32 v12, 3, v184
	v_lshl_add_u64 v[6:7], s[6:7], 0, v[16:17]
	v_readlane_b32 s1, v238, 39
	s_ashr_i32 s13, s0, 31
	s_mul_hi_i32 s6, s12, 0x1800
	s_mul_i32 s10, s12, 0x1800
	s_lshl_b64 s[0:1], s[12:13], 9
	v_or_b32_e32 v18, s10, v12
	v_mov_b32_e32 v19, s6
	s_mov_b64 s[6:7], 0xa800400
	v_and_b32_e32 v14, 0x300, v16
	v_lshlrev_b32_e32 v3, 4, v3
	v_or_b32_e32 v8, s0, v12
	s_lshl_b64 s[2:3], s[12:13], 10
	v_lshl_add_u64 v[12:13], v[18:19], 0, s[6:7]
	v_or3_b32 v18, s10, v14, v3
	s_mov_b64 s[8:9], 0xa800680
	v_lshlrev_b32_e32 v2, 4, v185
	v_mov_b32_e32 v9, s1
	s_mov_b64 s[0:1], 0x13800000
	s_ashr_i32 s97, s96, 31
	v_or_b32_e32 v10, s2, v16
	v_mov_b32_e32 v11, s3
	s_mov_b64 s[2:3], 0x12800000
	v_lshl_add_u64 v[14:15], v[18:19], 0, s[8:9]
	v_or_b32_e32 v18, s10, v16
	s_mov_b64 s[8:9], 0xa800000
	s_mov_b32 s10, s12
	v_lshrrev_b32_e32 v1, 4, v184
	v_bfe_u32 v0, v185, 2, 2
	v_and_b32_e32 v2, 48, v2
	v_readlane_b32 s61, v238, 6
	v_readlane_b32 s64, v238, 9
	v_readlane_b32 s65, v238, 10
	v_readlane_b32 s68, v238, 13
	v_readlane_b32 s69, v238, 14
	v_readlane_b32 s72, v238, 17
	v_readlane_b32 s73, v238, 18
	v_readlane_b32 s74, v238, 19
	v_readlane_b32 s75, v238, 20
	v_lshl_add_u64 v[8:9], v[8:9], 0, s[0:1]
	s_lshl_b64 s[0:1], s[96:97], 9
	v_lshl_add_u64 v[10:11], v[10:11], 0, s[2:3]
	s_lshl_b64 s[2:3], s[96:97], 10
	s_mul_hi_i32 s7, s96, 0x1800
	s_mul_i32 s6, s96, 0x1800
	v_lshl_add_u64 v[16:17], v[18:19], 0, s[8:9]
	v_mov_b32_e32 v3, 0x358637bd
	s_mov_b32 s8, 0x800000
	v_writelane_b32 v238, s10, 38
	s_mov_b32 s9, s12
	s_nop 0
	v_writelane_b32 v238, s11, 39
	global_load_dwordx4 v[60:63], v[4:5], off
	global_load_dwordx4 v[64:67], v[4:5], off offset:16
	global_load_dwordx4 v[68:71], v[6:7], off
	s_cmp_lg_u32 s96, 0x800
	s_cbranch_scc1 .LBB0_602
	s_cmpk_gt_i32 s9, 0x7ff
	s_cbranch_scc1 .LBB0_602
	v_lshl_add_u64 v[18:19], s[86:87], 0, v[14:15]
	v_lshl_add_u64 v[22:23], s[86:87], 0, v[16:17]
	v_lshl_add_u64 v[32:33], s[86:87], 0, v[12:13]
	global_load_dwordx4 v[52:55], v[18:19], off
	global_load_dwordx4 v[46:49], v[22:23], off
	global_load_dwordx2 v[50:51], v[32:33], off
	v_lshl_add_u64 v[12:13], v[12:13], 0, s[6:7]
	v_lshl_add_u64 v[14:15], v[14:15], 0, s[6:7]
	v_lshl_add_u64 v[16:17], v[16:17], 0, s[6:7]
	v_lshl_add_u64 v[18:19], s[86:87], 0, v[14:15]
	v_lshl_add_u64 v[22:23], s[86:87], 0, v[16:17]
	v_lshl_add_u64 v[32:33], s[86:87], 0, v[12:13]
	global_load_dwordx4 v[86:89], v[18:19], off
	global_load_dwordx4 v[90:93], v[22:23], off
	global_load_dwordx2 v[94:95], v[32:33], off
	v_lshl_add_u64 v[12:13], v[12:13], 0, s[6:7]
	v_lshl_add_u64 v[14:15], v[14:15], 0, s[6:7]
	v_lshl_add_u64 v[16:17], v[16:17], 0, s[6:7]
	v_lshl_add_u64 v[18:19], s[86:87], 0, v[14:15]
	v_lshl_add_u64 v[22:23], s[86:87], 0, v[16:17]
	v_lshl_add_u64 v[32:33], s[86:87], 0, v[12:13]
	global_load_dwordx4 v[96:99], v[18:19], off
	global_load_dwordx4 v[100:103], v[22:23], off
	global_load_dwordx2 v[104:105], v[32:33], off
	v_lshl_add_u64 v[12:13], v[12:13], 0, s[6:7]
	v_lshl_add_u64 v[14:15], v[14:15], 0, s[6:7]
	v_lshl_add_u64 v[16:17], v[16:17], 0, s[6:7]
	v_lshl_add_u64 v[18:19], s[86:87], 0, v[14:15]
	v_lshl_add_u64 v[22:23], s[86:87], 0, v[16:17]
	v_lshl_add_u64 v[32:33], s[86:87], 0, v[12:13]
	global_load_dwordx4 v[120:123], v[18:19], off
	global_load_dwordx4 v[124:127], v[22:23], off
	global_load_dwordx2 v[128:129], v[32:33], off
	v_lshl_add_u64 v[12:13], v[12:13], 0, s[6:7]
	v_lshl_add_u64 v[14:15], v[14:15], 0, s[6:7]
	v_lshl_add_u64 v[16:17], v[16:17], 0, s[6:7]
	v_lshl_add_u64 v[18:19], s[86:87], 0, v[14:15]
	v_lshl_add_u64 v[22:23], s[86:87], 0, v[16:17]
	v_lshl_add_u64 v[32:33], s[86:87], 0, v[12:13]
	global_load_dwordx4 v[130:133], v[18:19], off
	global_load_dwordx4 v[134:137], v[22:23], off
	global_load_dwordx2 v[138:139], v[32:33], off
	v_lshl_add_u64 v[12:13], v[12:13], 0, s[6:7]
	v_lshl_add_u64 v[14:15], v[14:15], 0, s[6:7]
	v_lshl_add_u64 v[16:17], v[16:17], 0, s[6:7]
	v_lshl_add_u64 v[18:19], s[86:87], 0, v[14:15]
	v_lshl_add_u64 v[22:23], s[86:87], 0, v[16:17]
	v_lshl_add_u64 v[32:33], s[86:87], 0, v[12:13]
	global_load_dwordx4 v[148:151], v[18:19], off
	global_load_dwordx4 v[152:155], v[22:23], off
	global_load_dwordx2 v[156:157], v[32:33], off
	v_lshl_add_u64 v[12:13], v[12:13], 0, s[6:7]
	v_lshl_add_u64 v[14:15], v[14:15], 0, s[6:7]
	v_lshl_add_u64 v[16:17], v[16:17], 0, s[6:7]
	v_lshl_add_u64 v[18:19], s[86:87], 0, v[14:15]
	v_lshl_add_u64 v[22:23], s[86:87], 0, v[16:17]
	v_lshl_add_u64 v[32:33], s[86:87], 0, v[12:13]
	global_load_dwordx4 v[166:169], v[18:19], off
	global_load_dwordx4 v[170:173], v[22:23], off
	global_load_dwordx2 v[174:175], v[32:33], off
	v_lshl_add_u64 v[12:13], v[12:13], 0, s[6:7]
	v_lshl_add_u64 v[14:15], v[14:15], 0, s[6:7]
	v_lshl_add_u64 v[16:17], v[16:17], 0, s[6:7]
	v_lshl_add_u64 v[18:19], s[86:87], 0, v[14:15]
	v_lshl_add_u64 v[22:23], s[86:87], 0, v[16:17]
	v_lshl_add_u64 v[32:33], s[86:87], 0, v[12:13]
	global_load_dwordx4 v[140:143], v[18:19], off
	global_load_dwordx4 v[158:161], v[22:23], off
	global_load_dwordx2 v[162:163], v[32:33], off
	v_lshl_add_u64 v[12:13], v[12:13], 0, s[6:7]
	v_lshl_add_u64 v[14:15], v[14:15], 0, s[6:7]
	v_lshl_add_u64 v[16:17], v[16:17], 0, s[6:7]
	s_ashr_i32 s11, s9, 9
	s_and_b32 s11, s11, 0x7fffffc
	s_bfe_u32 s10, s9, 0x50006
	v_or_b32_e32 v24, s11, v1
	v_lshl_or_b32 v24, v24, 5, s10
	v_ashrrev_i32_e32 v25, 31, v24
	s_lshr_b32 s12, s9, 2
	v_lshlrev_b64 v[24:25], 4, v[24:25]
	v_and_or_b32 v24, s12, 12, v24
	v_or_b32_e32 v24, v24, v0
	v_lshlrev_b64 v[24:25], 6, v[24:25]
	v_or_b32_e32 v24, v24, v2
	v_and_or_b32 v24, s9, 15, v24
	v_lshl_add_u64 v[24:25], v[24:25], 4, s[40:41]
	v_lshl_add_u64 v[30:31], s[86:87], 0, v[10:11]
	s_add_i32 s9, s9, s96
	v_lshl_add_u64 v[10:11], v[10:11], 0, s[2:3]
	s_waitcnt vmcnt(23)
; __device__ __forceinline__ unsigned pk2(float lo, float hi) { f32x2_t v = {lo, hi}; bf16x2_t b = __builtin_convertvector(v, bf16x2_t); return __builtin_bit_cast(unsigned, b); }
; __global__ void __launch_bounds__(512, 2) mega_fwd(Args args) {
;     ...
;                 const int h_ = lane >> 4, pc = lane & 15, fr_ = m & 15, fw_ = (m >> 4) & 3, ch_ = (m >> 6) & 31, b_ = m >> 11;
;                 const u32x4 gqv = *(const u32x4*)(zr + ZGQ + h_ * 128 + pc * 8);
;                 *(u32x4*)(H + ((((size_t)((b_ * 4 + h_) * 32 + ch_) * 4 + fw_) * 4 + (pc >> 2)) * 64 + (pc & 3) * 16 + fr_) * 8) = gqv;
;             }
;             {
;                 const u32x4 u = *(const u32x4*)(zr + ZQ + lane * 8);
;                 float v[8] = {bflo(u.x), bfhi(u.x), bflo(u.y), bfhi(u.y), bflo(u.z), bfhi(u.z), bflo(u.w), bfhi(u.w)};
;                 float sq = 0.f;
; #pragma unroll
;                 for (int e = 0; e < 8; ++e) sq += v[e] * v[e];
;                 const float r = rsqrtf(wave_sum(sq) * (1.f / 512.f) + EPS);
;                 const f32x4 g0 = *(const f32x4*)(args.in[9] + lane * 8), g1 = *(const f32x4*)(args.in[9] + lane * 8 + 4);
;                 u32x4 w; w.x = pk2(v[0] * r * g0.x, v[1] * r * g0.y); w.y = pk2(v[2] * r * g0.z, v[3] * r * g0.w); w.z = pk2(v[4] * r * g1.x, v[5] * r * g1.y); w.w = pk2(v[6] * r * g1.z, v[7] * r * g1.w);
;                 *(u32x4*)(QA + (size_t)m * 512 + lane * 8) = w;
;             }
;             {
;                 const u32x2 u = *(const u32x2*)(zr + ZKV + lane * 4);
;                 const float v0 = bflo(u.x), v1 = bfhi(u.x), v2 = bflo(u.y), v3 = bfhi(u.y);
;                 const float r = rsqrtf(wave_sum(v0 * v0 + v1 * v1 + v2 * v2 + v3 * v3) * (1.f / 256.f) + EPS);
;                 const f32x4 g0 = *(const f32x4*)(args.in[11] + lane * 4);
;                 u32x2 w; w.x = pk2(v0 * r * g0.x, v1 * r * g0.y); w.y = pk2(v2 * r * g0.z, v3 * r * g0.w);
;                 *(u32x2*)(KVA + (size_t)m * 256 + lane * 4) = w;
;             }
	global_store_dwordx4 v[24:25], v[52:55], off
	s_waitcnt vmcnt(23)
	v_lshlrev_b32_e32 v38, 16, v46
	v_and_b32_e32 v39, 0xffff0000, v46
	v_lshlrev_b32_e32 v34, 16, v49
	v_and_b32_e32 v35, 0xffff0000, v49
	v_lshlrev_b32_e32 v36, 16, v48
	v_and_b32_e32 v37, 0xffff0000, v48
	v_lshlrev_b32_e32 v20, 16, v47
	v_and_b32_e32 v21, 0xffff0000, v47
	v_pk_mul_f32 v[44:45], v[38:39], v[38:39]
	v_pk_mul_f32 v[42:43], v[20:21], v[20:21]
	v_add_f32_e32 v44, v44, v45
	v_add_f32_e32 v42, v44, v42
	v_pk_mul_f32 v[40:41], v[36:37], v[36:37]
	v_add_f32_e32 v42, v42, v43
	v_add_f32_e32 v40, v42, v40
	v_pk_mul_f32 v[18:19], v[34:35], v[34:35]
	v_add_f32_e32 v40, v40, v41
	v_add_f32_e32 v18, v40, v18
	v_add_f32_e32 v18, v18, v19
	s_nop 1
	v_add_f32_dpp v18, v18, v18 quad_perm:[1,0,3,2] row_mask:0xf bank_mask:0xf bound_ctrl:1
	s_nop 1
	v_add_f32_dpp v18, v18, v18 quad_perm:[2,3,0,1] row_mask:0xf bank_mask:0xf bound_ctrl:1
	s_nop 1
	v_add_f32_dpp v18, v18, v18 row_half_mirror row_mask:0xf bank_mask:0xf bound_ctrl:1
	s_nop 1
	v_add_f32_dpp v18, v18, v18 row_mirror row_mask:0xf bank_mask:0xf bound_ctrl:1
	s_nop 0
	v_readlane_b32 s12, v18, 16
	v_readlane_b32 s13, v18, 48
	v_readlane_b32 s10, v18, 0
	v_readlane_b32 s11, v18, 32
	v_mov_b32_e32 v18, s12
	v_mov_b32_e32 v19, s13
	v_pk_add_f32 v[18:19], s[10:11], v[18:19]
	s_nop 0
	v_add_f32_e32 v18, v18, v19
	v_fmamk_f32 v18, v18, 0x3b000000, v3
	v_mul_f32_e32 v19, 0x4b800000, v18
	v_cmp_gt_f32_e32 vcc, s8, v18
	s_nop 1
	v_cndmask_b32_e32 v18, v18, v19, vcc
	v_rsq_f32_e32 v18, v18
	s_nop 0
	v_mul_f32_e32 v19, 0x45800000, v18
	v_cndmask_b32_e32 v18, v18, v19, vcc
	v_pk_mul_f32 v[38:39], v[18:19], v[38:39] op_sel_hi:[0,1]
	v_pk_mul_f32 v[20:21], v[18:19], v[20:21] op_sel_hi:[0,1]
	v_pk_mul_f32 v[36:37], v[18:19], v[36:37] op_sel_hi:[0,1]
	v_pk_mul_f32 v[18:19], v[18:19], v[34:35] op_sel_hi:[0,1]
	v_pk_mul_f32 v[22:23], v[60:61], v[38:39]
	v_pk_mul_f32 v[20:21], v[62:63], v[20:21]
	v_pk_mul_f32 v[24:25], v[64:65], v[36:37]
	v_pk_mul_f32 v[26:27], v[66:67], v[18:19]
	v_cvt_pk_bf16_f32 v18, v22, v23
	v_cvt_pk_bf16_f32 v19, v20, v21
	v_cvt_pk_bf16_f32 v20, v24, v25
	v_cvt_pk_bf16_f32 v21, v26, v27
	global_store_dwordx4 v[30:31], v[18:21], off
	v_lshl_add_u64 v[24:25], s[86:87], 0, v[8:9]
	v_lshl_add_u64 v[8:9], v[8:9], 0, s[0:1]
	s_waitcnt vmcnt(23)
	v_lshlrev_b32_e32 v28, 16, v50
	v_and_b32_e32 v29, 0xffff0000, v50
	v_lshlrev_b32_e32 v26, 16, v51
	v_and_b32_e32 v27, 0xffff0000, v51
	v_pk_mul_f32 v[30:31], v[28:29], v[28:29]
	v_pk_mul_f32 v[22:23], v[26:27], v[26:27]
	v_add_f32_e32 v30, v30, v31
	v_add_f32_e32 v22, v22, v30
	v_add_f32_e32 v22, v23, v22
	s_nop 1
	v_add_f32_dpp v22, v22, v22 quad_perm:[1,0,3,2] row_mask:0xf bank_mask:0xf bound_ctrl:1
	s_nop 1
	v_add_f32_dpp v22, v22, v22 quad_perm:[2,3,0,1] row_mask:0xf bank_mask:0xf bound_ctrl:1
	s_nop 1
	v_add_f32_dpp v22, v22, v22 row_half_mirror row_mask:0xf bank_mask:0xf bound_ctrl:1
	s_nop 1
	v_add_f32_dpp v22, v22, v22 row_mirror row_mask:0xf bank_mask:0xf bound_ctrl:1
	s_nop 0
	v_readlane_b32 s12, v22, 16
	v_readlane_b32 s13, v22, 48
	v_readlane_b32 s10, v22, 0
	v_readlane_b32 s11, v22, 32
	v_mov_b32_e32 v22, s12
	v_mov_b32_e32 v23, s13
	v_pk_add_f32 v[22:23], s[10:11], v[22:23]
	s_nop 0
	v_add_f32_e32 v22, v22, v23
	v_fmamk_f32 v22, v22, 0x3b800000, v3
	v_mul_f32_e32 v23, 0x4b800000, v22
	v_cmp_gt_f32_e32 vcc, s8, v22
	s_nop 1
	v_cndmask_b32_e32 v22, v22, v23, vcc
	v_rsq_f32_e32 v22, v22
	s_nop 0
	v_mul_f32_e32 v23, 0x45800000, v22
	v_cndmask_b32_e32 v22, v22, v23, vcc
	v_pk_mul_f32 v[28:29], v[22:23], v[28:29] op_sel_hi:[0,1]
	v_pk_mul_f32 v[22:23], v[22:23], v[26:27] op_sel_hi:[0,1]
	v_pk_mul_f32 v[18:19], v[68:69], v[28:29]
	v_pk_mul_f32 v[20:21], v[70:71], v[22:23]
	v_cvt_pk_bf16_f32 v18, v18, v19
	v_cvt_pk_bf16_f32 v19, v20, v21
	global_store_dwordx2 v[24:25], v[18:19], off
	s_ashr_i32 s11, s9, 9
	s_and_b32 s11, s11, 0x7fffffc
	s_bfe_u32 s10, s9, 0x50006
	v_or_b32_e32 v24, s11, v1
	v_lshl_or_b32 v24, v24, 5, s10
	v_ashrrev_i32_e32 v25, 31, v24
	s_lshr_b32 s12, s9, 2
	v_lshlrev_b64 v[24:25], 4, v[24:25]
	v_and_or_b32 v24, s12, 12, v24
	v_or_b32_e32 v24, v24, v0
	v_lshlrev_b64 v[24:25], 6, v[24:25]
	v_or_b32_e32 v24, v24, v2
	v_and_or_b32 v24, s9, 15, v24
	v_lshl_add_u64 v[24:25], v[24:25], 4, s[40:41]
	v_lshl_add_u64 v[30:31], s[86:87], 0, v[10:11]
	s_add_i32 s9, s9, s96
	v_lshl_add_u64 v[10:11], v[10:11], 0, s[2:3]
	s_waitcnt vmcnt(23)
	global_store_dwordx4 v[24:25], v[86:89], off
	s_waitcnt vmcnt(23)
	v_lshlrev_b32_e32 v38, 16, v90
	v_and_b32_e32 v39, 0xffff0000, v90
	v_lshlrev_b32_e32 v34, 16, v93
	v_and_b32_e32 v35, 0xffff0000, v93
	v_lshlrev_b32_e32 v36, 16, v92
	v_and_b32_e32 v37, 0xffff0000, v92
	v_lshlrev_b32_e32 v20, 16, v91
	v_and_b32_e32 v21, 0xffff0000, v91
	v_pk_mul_f32 v[44:45], v[38:39], v[38:39]
	v_pk_mul_f32 v[42:43], v[20:21], v[20:21]
	v_add_f32_e32 v44, v44, v45
	v_add_f32_e32 v42, v44, v42
	v_pk_mul_f32 v[40:41], v[36:37], v[36:37]
	v_add_f32_e32 v42, v42, v43
	v_add_f32_e32 v40, v42, v40
	v_pk_mul_f32 v[18:19], v[34:35], v[34:35]
	v_add_f32_e32 v40, v40, v41
	v_add_f32_e32 v18, v40, v18
	v_add_f32_e32 v18, v18, v19
	s_nop 1
	v_add_f32_dpp v18, v18, v18 quad_perm:[1,0,3,2] row_mask:0xf bank_mask:0xf bound_ctrl:1
	s_nop 1
	v_add_f32_dpp v18, v18, v18 quad_perm:[2,3,0,1] row_mask:0xf bank_mask:0xf bound_ctrl:1
	s_nop 1
	v_add_f32_dpp v18, v18, v18 row_half_mirror row_mask:0xf bank_mask:0xf bound_ctrl:1
	s_nop 1
	v_add_f32_dpp v18, v18, v18 row_mirror row_mask:0xf bank_mask:0xf bound_ctrl:1
	s_nop 0
	v_readlane_b32 s12, v18, 16
	v_readlane_b32 s13, v18, 48
	v_readlane_b32 s10, v18, 0
	v_readlane_b32 s11, v18, 32
	v_mov_b32_e32 v18, s12
	v_mov_b32_e32 v19, s13
	v_pk_add_f32 v[18:19], s[10:11], v[18:19]
	s_nop 0
	v_add_f32_e32 v18, v18, v19
	v_fmamk_f32 v18, v18, 0x3b000000, v3
	v_mul_f32_e32 v19, 0x4b800000, v18
	v_cmp_gt_f32_e32 vcc, s8, v18
	s_nop 1
	v_cndmask_b32_e32 v18, v18, v19, vcc
	v_rsq_f32_e32 v18, v18
	s_nop 0
	v_mul_f32_e32 v19, 0x45800000, v18
	v_cndmask_b32_e32 v18, v18, v19, vcc
	v_pk_mul_f32 v[38:39], v[18:19], v[38:39] op_sel_hi:[0,1]
	v_pk_mul_f32 v[20:21], v[18:19], v[20:21] op_sel_hi:[0,1]
	v_pk_mul_f32 v[36:37], v[18:19], v[36:37] op_sel_hi:[0,1]
	v_pk_mul_f32 v[18:19], v[18:19], v[34:35] op_sel_hi:[0,1]
	v_pk_mul_f32 v[22:23], v[60:61], v[38:39]
	v_pk_mul_f32 v[20:21], v[62:63], v[20:21]
	v_pk_mul_f32 v[24:25], v[64:65], v[36:37]
	v_pk_mul_f32 v[26:27], v[66:67], v[18:19]
	v_cvt_pk_bf16_f32 v18, v22, v23
	v_cvt_pk_bf16_f32 v19, v20, v21
	v_cvt_pk_bf16_f32 v20, v24, v25
	v_cvt_pk_bf16_f32 v21, v26, v27
	global_store_dwordx4 v[30:31], v[18:21], off
	v_lshl_add_u64 v[24:25], s[86:87], 0, v[8:9]
	v_lshl_add_u64 v[8:9], v[8:9], 0, s[0:1]
	s_waitcnt vmcnt(23)
; __device__ __forceinline__ unsigned pk2(float lo, float hi) { f32x2_t v = {lo, hi}; bf16x2_t b = __builtin_convertvector(v, bf16x2_t); return __builtin_bit_cast(unsigned, b); }
; __global__ void __launch_bounds__(512, 2) mega_fwd(Args args) {
;     ...
;                 const int h_ = lane >> 4, pc = lane & 15, fr_ = m & 15, fw_ = (m >> 4) & 3, ch_ = (m >> 6) & 31, b_ = m >> 11;
;                 const u32x4 gqv = *(const u32x4*)(zr + ZGQ + h_ * 128 + pc * 8);
;                 *(u32x4*)(H + ((((size_t)((b_ * 4 + h_) * 32 + ch_) * 4 + fw_) * 4 + (pc >> 2)) * 64 + (pc & 3) * 16 + fr_) * 8) = gqv;
;             }
;             {
;                 const u32x4 u = *(const u32x4*)(zr + ZQ + lane * 8);
;                 float v[8] = {bflo(u.x), bfhi(u.x), bflo(u.y), bfhi(u.y), bflo(u.z), bfhi(u.z), bflo(u.w), bfhi(u.w)};
;                 float sq = 0.f;
; #pragma unroll
;                 for (int e = 0; e < 8; ++e) sq += v[e] * v[e];
;                 const float r = rsqrtf(wave_sum(sq) * (1.f / 512.f) + EPS);
;                 const f32x4 g0 = *(const f32x4*)(args.in[9] + lane * 8), g1 = *(const f32x4*)(args.in[9] + lane * 8 + 4);
;                 u32x4 w; w.x = pk2(v[0] * r * g0.x, v[1] * r * g0.y); w.y = pk2(v[2] * r * g0.z, v[3] * r * g0.w); w.z = pk2(v[4] * r * g1.x, v[5] * r * g1.y); w.w = pk2(v[6] * r * g1.z, v[7] * r * g1.w);
;                 *(u32x4*)(QA + (size_t)m * 512 + lane * 8) = w;
;             }
;             {
;                 const u32x2 u = *(const u32x2*)(zr + ZKV + lane * 4);
;                 const float v0 = bflo(u.x), v1 = bfhi(u.x), v2 = bflo(u.y), v3 = bfhi(u.y);
;                 const float r = rsqrtf(wave_sum(v0 * v0 + v1 * v1 + v2 * v2 + v3 * v3) * (1.f / 256.f) + EPS);
;                 const f32x4 g0 = *(const f32x4*)(args.in[11] + lane * 4);
;                 u32x2 w; w.x = pk2(v0 * r * g0.x, v1 * r * g0.y); w.y = pk2(v2 * r * g0.z, v3 * r * g0.w);
;                 *(u32x2*)(KVA + (size_t)m * 256 + lane * 4) = w;
;             }
	v_lshlrev_b32_e32 v28, 16, v94
	v_and_b32_e32 v29, 0xffff0000, v94
	v_lshlrev_b32_e32 v26, 16, v95
	v_and_b32_e32 v27, 0xffff0000, v95
	v_pk_mul_f32 v[30:31], v[28:29], v[28:29]
	v_pk_mul_f32 v[22:23], v[26:27], v[26:27]
	v_add_f32_e32 v30, v30, v31
	v_add_f32_e32 v22, v22, v30
	v_add_f32_e32 v22, v23, v22
	s_nop 1
	v_add_f32_dpp v22, v22, v22 quad_perm:[1,0,3,2] row_mask:0xf bank_mask:0xf bound_ctrl:1
	s_nop 1
	v_add_f32_dpp v22, v22, v22 quad_perm:[2,3,0,1] row_mask:0xf bank_mask:0xf bound_ctrl:1
	s_nop 1
	v_add_f32_dpp v22, v22, v22 row_half_mirror row_mask:0xf bank_mask:0xf bound_ctrl:1
	s_nop 1
	v_add_f32_dpp v22, v22, v22 row_mirror row_mask:0xf bank_mask:0xf bound_ctrl:1
	s_nop 0
	v_readlane_b32 s12, v22, 16
	v_readlane_b32 s13, v22, 48
	v_readlane_b32 s10, v22, 0
	v_readlane_b32 s11, v22, 32
	v_mov_b32_e32 v22, s12
	v_mov_b32_e32 v23, s13
	v_pk_add_f32 v[22:23], s[10:11], v[22:23]
	s_nop 0
	v_add_f32_e32 v22, v22, v23
	v_fmamk_f32 v22, v22, 0x3b800000, v3
	v_mul_f32_e32 v23, 0x4b800000, v22
	v_cmp_gt_f32_e32 vcc, s8, v22
	s_nop 1
	v_cndmask_b32_e32 v22, v22, v23, vcc
	v_rsq_f32_e32 v22, v22
	s_nop 0
	v_mul_f32_e32 v23, 0x45800000, v22
	v_cndmask_b32_e32 v22, v22, v23, vcc
	v_pk_mul_f32 v[28:29], v[22:23], v[28:29] op_sel_hi:[0,1]
	v_pk_mul_f32 v[22:23], v[22:23], v[26:27] op_sel_hi:[0,1]
	v_pk_mul_f32 v[18:19], v[68:69], v[28:29]
	v_pk_mul_f32 v[20:21], v[70:71], v[22:23]
	v_cvt_pk_bf16_f32 v18, v18, v19
	v_cvt_pk_bf16_f32 v19, v20, v21
	global_store_dwordx2 v[24:25], v[18:19], off
	s_ashr_i32 s11, s9, 9
	s_and_b32 s11, s11, 0x7fffffc
	s_bfe_u32 s10, s9, 0x50006
	v_or_b32_e32 v24, s11, v1
	v_lshl_or_b32 v24, v24, 5, s10
	v_ashrrev_i32_e32 v25, 31, v24
	s_lshr_b32 s12, s9, 2
	v_lshlrev_b64 v[24:25], 4, v[24:25]
	v_and_or_b32 v24, s12, 12, v24
	v_or_b32_e32 v24, v24, v0
	v_lshlrev_b64 v[24:25], 6, v[24:25]
	v_or_b32_e32 v24, v24, v2
	v_and_or_b32 v24, s9, 15, v24
	v_lshl_add_u64 v[24:25], v[24:25], 4, s[40:41]
	v_lshl_add_u64 v[30:31], s[86:87], 0, v[10:11]
	s_add_i32 s9, s9, s96
	v_lshl_add_u64 v[10:11], v[10:11], 0, s[2:3]
	s_waitcnt vmcnt(23)
	global_store_dwordx4 v[24:25], v[96:99], off
	s_waitcnt vmcnt(23)
	v_lshlrev_b32_e32 v38, 16, v100
	v_and_b32_e32 v39, 0xffff0000, v100
	v_lshlrev_b32_e32 v34, 16, v103
	v_and_b32_e32 v35, 0xffff0000, v103
	v_lshlrev_b32_e32 v36, 16, v102
	v_and_b32_e32 v37, 0xffff0000, v102
	v_lshlrev_b32_e32 v20, 16, v101
	v_and_b32_e32 v21, 0xffff0000, v101
	v_pk_mul_f32 v[44:45], v[38:39], v[38:39]
	v_pk_mul_f32 v[42:43], v[20:21], v[20:21]
	v_add_f32_e32 v44, v44, v45
	v_add_f32_e32 v42, v44, v42
	v_pk_mul_f32 v[40:41], v[36:37], v[36:37]
	v_add_f32_e32 v42, v42, v43
	v_add_f32_e32 v40, v42, v40
	v_pk_mul_f32 v[18:19], v[34:35], v[34:35]
	v_add_f32_e32 v40, v40, v41
	v_add_f32_e32 v18, v40, v18
	v_add_f32_e32 v18, v18, v19
	s_nop 1
	v_add_f32_dpp v18, v18, v18 quad_perm:[1,0,3,2] row_mask:0xf bank_mask:0xf bound_ctrl:1
	s_nop 1
	v_add_f32_dpp v18, v18, v18 quad_perm:[2,3,0,1] row_mask:0xf bank_mask:0xf bound_ctrl:1
	s_nop 1
	v_add_f32_dpp v18, v18, v18 row_half_mirror row_mask:0xf bank_mask:0xf bound_ctrl:1
	s_nop 1
	v_add_f32_dpp v18, v18, v18 row_mirror row_mask:0xf bank_mask:0xf bound_ctrl:1
	s_nop 0
	v_readlane_b32 s12, v18, 16
	v_readlane_b32 s13, v18, 48
	v_readlane_b32 s10, v18, 0
	v_readlane_b32 s11, v18, 32
	v_mov_b32_e32 v18, s12
	v_mov_b32_e32 v19, s13
	v_pk_add_f32 v[18:19], s[10:11], v[18:19]
	s_nop 0
	v_add_f32_e32 v18, v18, v19
	v_fmamk_f32 v18, v18, 0x3b000000, v3
	v_mul_f32_e32 v19, 0x4b800000, v18
	v_cmp_gt_f32_e32 vcc, s8, v18
	s_nop 1
	v_cndmask_b32_e32 v18, v18, v19, vcc
	v_rsq_f32_e32 v18, v18
	s_nop 0
	v_mul_f32_e32 v19, 0x45800000, v18
	v_cndmask_b32_e32 v18, v18, v19, vcc
	v_pk_mul_f32 v[38:39], v[18:19], v[38:39] op_sel_hi:[0,1]
	v_pk_mul_f32 v[20:21], v[18:19], v[20:21] op_sel_hi:[0,1]
	v_pk_mul_f32 v[36:37], v[18:19], v[36:37] op_sel_hi:[0,1]
	v_pk_mul_f32 v[18:19], v[18:19], v[34:35] op_sel_hi:[0,1]
	v_pk_mul_f32 v[22:23], v[60:61], v[38:39]
	v_pk_mul_f32 v[20:21], v[62:63], v[20:21]
	v_pk_mul_f32 v[24:25], v[64:65], v[36:37]
	v_pk_mul_f32 v[26:27], v[66:67], v[18:19]
	v_cvt_pk_bf16_f32 v18, v22, v23
	v_cvt_pk_bf16_f32 v19, v20, v21
	v_cvt_pk_bf16_f32 v20, v24, v25
	v_cvt_pk_bf16_f32 v21, v26, v27
	global_store_dwordx4 v[30:31], v[18:21], off
	v_lshl_add_u64 v[24:25], s[86:87], 0, v[8:9]
	v_lshl_add_u64 v[8:9], v[8:9], 0, s[0:1]
	s_waitcnt vmcnt(23)
	v_lshlrev_b32_e32 v28, 16, v104
	v_and_b32_e32 v29, 0xffff0000, v104
	v_lshlrev_b32_e32 v26, 16, v105
	v_and_b32_e32 v27, 0xffff0000, v105
	v_pk_mul_f32 v[30:31], v[28:29], v[28:29]
	v_pk_mul_f32 v[22:23], v[26:27], v[26:27]
	v_add_f32_e32 v30, v30, v31
	v_add_f32_e32 v22, v22, v30
	v_add_f32_e32 v22, v23, v22
	s_nop 1
	v_add_f32_dpp v22, v22, v22 quad_perm:[1,0,3,2] row_mask:0xf bank_mask:0xf bound_ctrl:1
	s_nop 1
	v_add_f32_dpp v22, v22, v22 quad_perm:[2,3,0,1] row_mask:0xf bank_mask:0xf bound_ctrl:1
	s_nop 1
	v_add_f32_dpp v22, v22, v22 row_half_mirror row_mask:0xf bank_mask:0xf bound_ctrl:1
	s_nop 1
	v_add_f32_dpp v22, v22, v22 row_mirror row_mask:0xf bank_mask:0xf bound_ctrl:1
	s_nop 0
	v_readlane_b32 s12, v22, 16
	v_readlane_b32 s13, v22, 48
	v_readlane_b32 s10, v22, 0
	v_readlane_b32 s11, v22, 32
	v_mov_b32_e32 v22, s12
	v_mov_b32_e32 v23, s13
	v_pk_add_f32 v[22:23], s[10:11], v[22:23]
	s_nop 0
	v_add_f32_e32 v22, v22, v23
	v_fmamk_f32 v22, v22, 0x3b800000, v3
	v_mul_f32_e32 v23, 0x4b800000, v22
	v_cmp_gt_f32_e32 vcc, s8, v22
	s_nop 1
	v_cndmask_b32_e32 v22, v22, v23, vcc
	v_rsq_f32_e32 v22, v22
	s_nop 0
	v_mul_f32_e32 v23, 0x45800000, v22
	v_cndmask_b32_e32 v22, v22, v23, vcc
	v_pk_mul_f32 v[28:29], v[22:23], v[28:29] op_sel_hi:[0,1]
	v_pk_mul_f32 v[22:23], v[22:23], v[26:27] op_sel_hi:[0,1]
	v_pk_mul_f32 v[18:19], v[68:69], v[28:29]
	v_pk_mul_f32 v[20:21], v[70:71], v[22:23]
	v_cvt_pk_bf16_f32 v18, v18, v19
	v_cvt_pk_bf16_f32 v19, v20, v21
	global_store_dwordx2 v[24:25], v[18:19], off
	s_ashr_i32 s11, s9, 9
	s_and_b32 s11, s11, 0x7fffffc
	s_bfe_u32 s10, s9, 0x50006
	v_or_b32_e32 v24, s11, v1
	v_lshl_or_b32 v24, v24, 5, s10
	v_ashrrev_i32_e32 v25, 31, v24
	s_lshr_b32 s12, s9, 2
	v_lshlrev_b64 v[24:25], 4, v[24:25]
	v_and_or_b32 v24, s12, 12, v24
	v_or_b32_e32 v24, v24, v0
	v_lshlrev_b64 v[24:25], 6, v[24:25]
	v_or_b32_e32 v24, v24, v2
	v_and_or_b32 v24, s9, 15, v24
	v_lshl_add_u64 v[24:25], v[24:25], 4, s[40:41]
	v_lshl_add_u64 v[30:31], s[86:87], 0, v[10:11]
	s_add_i32 s9, s9, s96
	v_lshl_add_u64 v[10:11], v[10:11], 0, s[2:3]
	s_waitcnt vmcnt(23)
; __device__ __forceinline__ unsigned pk2(float lo, float hi) { f32x2_t v = {lo, hi}; bf16x2_t b = __builtin_convertvector(v, bf16x2_t); return __builtin_bit_cast(unsigned, b); }
; __global__ void __launch_bounds__(512, 2) mega_fwd(Args args) {
;     ...
;                 const int h_ = lane >> 4, pc = lane & 15, fr_ = m & 15, fw_ = (m >> 4) & 3, ch_ = (m >> 6) & 31, b_ = m >> 11;
;                 const u32x4 gqv = *(const u32x4*)(zr + ZGQ + h_ * 128 + pc * 8);
;                 *(u32x4*)(H + ((((size_t)((b_ * 4 + h_) * 32 + ch_) * 4 + fw_) * 4 + (pc >> 2)) * 64 + (pc & 3) * 16 + fr_) * 8) = gqv;
;             }
;             {
;                 const u32x4 u = *(const u32x4*)(zr + ZQ + lane * 8);
;                 float v[8] = {bflo(u.x), bfhi(u.x), bflo(u.y), bfhi(u.y), bflo(u.z), bfhi(u.z), bflo(u.w), bfhi(u.w)};
;                 float sq = 0.f;
; #pragma unroll
;                 for (int e = 0; e < 8; ++e) sq += v[e] * v[e];
;                 const float r = rsqrtf(wave_sum(sq) * (1.f / 512.f) + EPS);
;                 const f32x4 g0 = *(const f32x4*)(args.in[9] + lane * 8), g1 = *(const f32x4*)(args.in[9] + lane * 8 + 4);
;                 u32x4 w; w.x = pk2(v[0] * r * g0.x, v[1] * r * g0.y); w.y = pk2(v[2] * r * g0.z, v[3] * r * g0.w); w.z = pk2(v[4] * r * g1.x, v[5] * r * g1.y); w.w = pk2(v[6] * r * g1.z, v[7] * r * g1.w);
;                 *(u32x4*)(QA + (size_t)m * 512 + lane * 8) = w;
;             }
;             {
;                 const u32x2 u = *(const u32x2*)(zr + ZKV + lane * 4);
;                 const float v0 = bflo(u.x), v1 = bfhi(u.x), v2 = bflo(u.y), v3 = bfhi(u.y);
;                 const float r = rsqrtf(wave_sum(v0 * v0 + v1 * v1 + v2 * v2 + v3 * v3) * (1.f / 256.f) + EPS);
;                 const f32x4 g0 = *(const f32x4*)(args.in[11] + lane * 4);
;                 u32x2 w; w.x = pk2(v0 * r * g0.x, v1 * r * g0.y); w.y = pk2(v2 * r * g0.z, v3 * r * g0.w);
;                 *(u32x2*)(KVA + (size_t)m * 256 + lane * 4) = w;
;             }
	global_store_dwordx4 v[24:25], v[120:123], off
	s_waitcnt vmcnt(23)
	v_lshlrev_b32_e32 v38, 16, v124
	v_and_b32_e32 v39, 0xffff0000, v124
	v_lshlrev_b32_e32 v34, 16, v127
	v_and_b32_e32 v35, 0xffff0000, v127
	v_lshlrev_b32_e32 v36, 16, v126
	v_and_b32_e32 v37, 0xffff0000, v126
	v_lshlrev_b32_e32 v20, 16, v125
	v_and_b32_e32 v21, 0xffff0000, v125
	v_pk_mul_f32 v[44:45], v[38:39], v[38:39]
	v_pk_mul_f32 v[42:43], v[20:21], v[20:21]
	v_add_f32_e32 v44, v44, v45
	v_add_f32_e32 v42, v44, v42
	v_pk_mul_f32 v[40:41], v[36:37], v[36:37]
	v_add_f32_e32 v42, v42, v43
	v_add_f32_e32 v40, v42, v40
	v_pk_mul_f32 v[18:19], v[34:35], v[34:35]
	v_add_f32_e32 v40, v40, v41
	v_add_f32_e32 v18, v40, v18
	v_add_f32_e32 v18, v18, v19
	s_nop 1
	v_add_f32_dpp v18, v18, v18 quad_perm:[1,0,3,2] row_mask:0xf bank_mask:0xf bound_ctrl:1
	s_nop 1
	v_add_f32_dpp v18, v18, v18 quad_perm:[2,3,0,1] row_mask:0xf bank_mask:0xf bound_ctrl:1
	s_nop 1
	v_add_f32_dpp v18, v18, v18 row_half_mirror row_mask:0xf bank_mask:0xf bound_ctrl:1
	s_nop 1
	v_add_f32_dpp v18, v18, v18 row_mirror row_mask:0xf bank_mask:0xf bound_ctrl:1
	s_nop 0
	v_readlane_b32 s12, v18, 16
	v_readlane_b32 s13, v18, 48
	v_readlane_b32 s10, v18, 0
	v_readlane_b32 s11, v18, 32
	v_mov_b32_e32 v18, s12
	v_mov_b32_e32 v19, s13
	v_pk_add_f32 v[18:19], s[10:11], v[18:19]
	s_nop 0
	v_add_f32_e32 v18, v18, v19
	v_fmamk_f32 v18, v18, 0x3b000000, v3
	v_mul_f32_e32 v19, 0x4b800000, v18
	v_cmp_gt_f32_e32 vcc, s8, v18
	s_nop 1
	v_cndmask_b32_e32 v18, v18, v19, vcc
	v_rsq_f32_e32 v18, v18
	s_nop 0
	v_mul_f32_e32 v19, 0x45800000, v18
	v_cndmask_b32_e32 v18, v18, v19, vcc
	v_pk_mul_f32 v[38:39], v[18:19], v[38:39] op_sel_hi:[0,1]
	v_pk_mul_f32 v[20:21], v[18:19], v[20:21] op_sel_hi:[0,1]
	v_pk_mul_f32 v[36:37], v[18:19], v[36:37] op_sel_hi:[0,1]
	v_pk_mul_f32 v[18:19], v[18:19], v[34:35] op_sel_hi:[0,1]
	v_pk_mul_f32 v[22:23], v[60:61], v[38:39]
	v_pk_mul_f32 v[20:21], v[62:63], v[20:21]
	v_pk_mul_f32 v[24:25], v[64:65], v[36:37]
	v_pk_mul_f32 v[26:27], v[66:67], v[18:19]
	v_cvt_pk_bf16_f32 v18, v22, v23
	v_cvt_pk_bf16_f32 v19, v20, v21
	v_cvt_pk_bf16_f32 v20, v24, v25
	v_cvt_pk_bf16_f32 v21, v26, v27
	global_store_dwordx4 v[30:31], v[18:21], off
	v_lshl_add_u64 v[24:25], s[86:87], 0, v[8:9]
	v_lshl_add_u64 v[8:9], v[8:9], 0, s[0:1]
	s_waitcnt vmcnt(23)
	v_lshlrev_b32_e32 v28, 16, v128
	v_and_b32_e32 v29, 0xffff0000, v128
	v_lshlrev_b32_e32 v26, 16, v129
	v_and_b32_e32 v27, 0xffff0000, v129
	v_pk_mul_f32 v[30:31], v[28:29], v[28:29]
	v_pk_mul_f32 v[22:23], v[26:27], v[26:27]
	v_add_f32_e32 v30, v30, v31
	v_add_f32_e32 v22, v22, v30
	v_add_f32_e32 v22, v23, v22
	s_nop 1
	v_add_f32_dpp v22, v22, v22 quad_perm:[1,0,3,2] row_mask:0xf bank_mask:0xf bound_ctrl:1
	s_nop 1
	v_add_f32_dpp v22, v22, v22 quad_perm:[2,3,0,1] row_mask:0xf bank_mask:0xf bound_ctrl:1
	s_nop 1
	v_add_f32_dpp v22, v22, v22 row_half_mirror row_mask:0xf bank_mask:0xf bound_ctrl:1
	s_nop 1
	v_add_f32_dpp v22, v22, v22 row_mirror row_mask:0xf bank_mask:0xf bound_ctrl:1
	s_nop 0
	v_readlane_b32 s12, v22, 16
	v_readlane_b32 s13, v22, 48
	v_readlane_b32 s10, v22, 0
	v_readlane_b32 s11, v22, 32
	v_mov_b32_e32 v22, s12
	v_mov_b32_e32 v23, s13
	v_pk_add_f32 v[22:23], s[10:11], v[22:23]
	s_nop 0
	v_add_f32_e32 v22, v22, v23
	v_fmamk_f32 v22, v22, 0x3b800000, v3
	v_mul_f32_e32 v23, 0x4b800000, v22
	v_cmp_gt_f32_e32 vcc, s8, v22
	s_nop 1
	v_cndmask_b32_e32 v22, v22, v23, vcc
	v_rsq_f32_e32 v22, v22
	s_nop 0
	v_mul_f32_e32 v23, 0x45800000, v22
	v_cndmask_b32_e32 v22, v22, v23, vcc
	v_pk_mul_f32 v[28:29], v[22:23], v[28:29] op_sel_hi:[0,1]
	v_pk_mul_f32 v[22:23], v[22:23], v[26:27] op_sel_hi:[0,1]
	v_pk_mul_f32 v[18:19], v[68:69], v[28:29]
	v_pk_mul_f32 v[20:21], v[70:71], v[22:23]
	v_cvt_pk_bf16_f32 v18, v18, v19
	v_cvt_pk_bf16_f32 v19, v20, v21
	global_store_dwordx2 v[24:25], v[18:19], off
	s_ashr_i32 s11, s9, 9
	s_and_b32 s11, s11, 0x7fffffc
	s_bfe_u32 s10, s9, 0x50006
	v_or_b32_e32 v24, s11, v1
	v_lshl_or_b32 v24, v24, 5, s10
	v_ashrrev_i32_e32 v25, 31, v24
	s_lshr_b32 s12, s9, 2
	v_lshlrev_b64 v[24:25], 4, v[24:25]
	v_and_or_b32 v24, s12, 12, v24
	v_or_b32_e32 v24, v24, v0
	v_lshlrev_b64 v[24:25], 6, v[24:25]
	v_or_b32_e32 v24, v24, v2
	v_and_or_b32 v24, s9, 15, v24
	v_lshl_add_u64 v[24:25], v[24:25], 4, s[40:41]
	v_lshl_add_u64 v[30:31], s[86:87], 0, v[10:11]
	s_add_i32 s9, s9, s96
	v_lshl_add_u64 v[10:11], v[10:11], 0, s[2:3]
	s_waitcnt vmcnt(23)
	global_store_dwordx4 v[24:25], v[130:133], off
	s_waitcnt vmcnt(23)
	v_lshlrev_b32_e32 v38, 16, v134
	v_and_b32_e32 v39, 0xffff0000, v134
	v_lshlrev_b32_e32 v34, 16, v137
	v_and_b32_e32 v35, 0xffff0000, v137
	v_lshlrev_b32_e32 v36, 16, v136
	v_and_b32_e32 v37, 0xffff0000, v136
	v_lshlrev_b32_e32 v20, 16, v135
	v_and_b32_e32 v21, 0xffff0000, v135
	v_pk_mul_f32 v[44:45], v[38:39], v[38:39]
	v_pk_mul_f32 v[42:43], v[20:21], v[20:21]
	v_add_f32_e32 v44, v44, v45
	v_add_f32_e32 v42, v44, v42
	v_pk_mul_f32 v[40:41], v[36:37], v[36:37]
	v_add_f32_e32 v42, v42, v43
	v_add_f32_e32 v40, v42, v40
	v_pk_mul_f32 v[18:19], v[34:35], v[34:35]
	v_add_f32_e32 v40, v40, v41
	v_add_f32_e32 v18, v40, v18
	v_add_f32_e32 v18, v18, v19
	s_nop 1
	v_add_f32_dpp v18, v18, v18 quad_perm:[1,0,3,2] row_mask:0xf bank_mask:0xf bound_ctrl:1
	s_nop 1
	v_add_f32_dpp v18, v18, v18 quad_perm:[2,3,0,1] row_mask:0xf bank_mask:0xf bound_ctrl:1
	s_nop 1
	v_add_f32_dpp v18, v18, v18 row_half_mirror row_mask:0xf bank_mask:0xf bound_ctrl:1
	s_nop 1
	v_add_f32_dpp v18, v18, v18 row_mirror row_mask:0xf bank_mask:0xf bound_ctrl:1
	s_nop 0
	v_readlane_b32 s12, v18, 16
	v_readlane_b32 s13, v18, 48
	v_readlane_b32 s10, v18, 0
	v_readlane_b32 s11, v18, 32
	v_mov_b32_e32 v18, s12
	v_mov_b32_e32 v19, s13
	v_pk_add_f32 v[18:19], s[10:11], v[18:19]
	s_nop 0
	v_add_f32_e32 v18, v18, v19
	v_fmamk_f32 v18, v18, 0x3b000000, v3
	v_mul_f32_e32 v19, 0x4b800000, v18
	v_cmp_gt_f32_e32 vcc, s8, v18
	s_nop 1
	v_cndmask_b32_e32 v18, v18, v19, vcc
	v_rsq_f32_e32 v18, v18
	s_nop 0
	v_mul_f32_e32 v19, 0x45800000, v18
	v_cndmask_b32_e32 v18, v18, v19, vcc
	v_pk_mul_f32 v[38:39], v[18:19], v[38:39] op_sel_hi:[0,1]
	v_pk_mul_f32 v[20:21], v[18:19], v[20:21] op_sel_hi:[0,1]
	v_pk_mul_f32 v[36:37], v[18:19], v[36:37] op_sel_hi:[0,1]
	v_pk_mul_f32 v[18:19], v[18:19], v[34:35] op_sel_hi:[0,1]
	v_pk_mul_f32 v[22:23], v[60:61], v[38:39]
	v_pk_mul_f32 v[20:21], v[62:63], v[20:21]
	v_pk_mul_f32 v[24:25], v[64:65], v[36:37]
	v_pk_mul_f32 v[26:27], v[66:67], v[18:19]
	v_cvt_pk_bf16_f32 v18, v22, v23
	v_cvt_pk_bf16_f32 v19, v20, v21
	v_cvt_pk_bf16_f32 v20, v24, v25
	v_cvt_pk_bf16_f32 v21, v26, v27
	global_store_dwordx4 v[30:31], v[18:21], off
	v_lshl_add_u64 v[24:25], s[86:87], 0, v[8:9]
	v_lshl_add_u64 v[8:9], v[8:9], 0, s[0:1]
	s_waitcnt vmcnt(23)
; __device__ __forceinline__ unsigned pk2(float lo, float hi) { f32x2_t v = {lo, hi}; bf16x2_t b = __builtin_convertvector(v, bf16x2_t); return __builtin_bit_cast(unsigned, b); }
; __global__ void __launch_bounds__(512, 2) mega_fwd(Args args) {
;     ...
;                 const int h_ = lane >> 4, pc = lane & 15, fr_ = m & 15, fw_ = (m >> 4) & 3, ch_ = (m >> 6) & 31, b_ = m >> 11;
;                 const u32x4 gqv = *(const u32x4*)(zr + ZGQ + h_ * 128 + pc * 8);
;                 *(u32x4*)(H + ((((size_t)((b_ * 4 + h_) * 32 + ch_) * 4 + fw_) * 4 + (pc >> 2)) * 64 + (pc & 3) * 16 + fr_) * 8) = gqv;
;             }
;             {
;                 const u32x4 u = *(const u32x4*)(zr + ZQ + lane * 8);
;                 float v[8] = {bflo(u.x), bfhi(u.x), bflo(u.y), bfhi(u.y), bflo(u.z), bfhi(u.z), bflo(u.w), bfhi(u.w)};
;                 float sq = 0.f;
; #pragma unroll
;                 for (int e = 0; e < 8; ++e) sq += v[e] * v[e];
;                 const float r = rsqrtf(wave_sum(sq) * (1.f / 512.f) + EPS);
;                 const f32x4 g0 = *(const f32x4*)(args.in[9] + lane * 8), g1 = *(const f32x4*)(args.in[9] + lane * 8 + 4);
;                 u32x4 w; w.x = pk2(v[0] * r * g0.x, v[1] * r * g0.y); w.y = pk2(v[2] * r * g0.z, v[3] * r * g0.w); w.z = pk2(v[4] * r * g1.x, v[5] * r * g1.y); w.w = pk2(v[6] * r * g1.z, v[7] * r * g1.w);
;                 *(u32x4*)(QA + (size_t)m * 512 + lane * 8) = w;
;             }
;             {
;                 const u32x2 u = *(const u32x2*)(zr + ZKV + lane * 4);
;                 const float v0 = bflo(u.x), v1 = bfhi(u.x), v2 = bflo(u.y), v3 = bfhi(u.y);
;                 const float r = rsqrtf(wave_sum(v0 * v0 + v1 * v1 + v2 * v2 + v3 * v3) * (1.f / 256.f) + EPS);
;                 const f32x4 g0 = *(const f32x4*)(args.in[11] + lane * 4);
;                 u32x2 w; w.x = pk2(v0 * r * g0.x, v1 * r * g0.y); w.y = pk2(v2 * r * g0.z, v3 * r * g0.w);
;                 *(u32x2*)(KVA + (size_t)m * 256 + lane * 4) = w;
;             }
	v_lshlrev_b32_e32 v28, 16, v138
	v_and_b32_e32 v29, 0xffff0000, v138
	v_lshlrev_b32_e32 v26, 16, v139
	v_and_b32_e32 v27, 0xffff0000, v139
	v_pk_mul_f32 v[30:31], v[28:29], v[28:29]
	v_pk_mul_f32 v[22:23], v[26:27], v[26:27]
	v_add_f32_e32 v30, v30, v31
	v_add_f32_e32 v22, v22, v30
	v_add_f32_e32 v22, v23, v22
	s_nop 1
	v_add_f32_dpp v22, v22, v22 quad_perm:[1,0,3,2] row_mask:0xf bank_mask:0xf bound_ctrl:1
	s_nop 1
	v_add_f32_dpp v22, v22, v22 quad_perm:[2,3,0,1] row_mask:0xf bank_mask:0xf bound_ctrl:1
	s_nop 1
	v_add_f32_dpp v22, v22, v22 row_half_mirror row_mask:0xf bank_mask:0xf bound_ctrl:1
	s_nop 1
	v_add_f32_dpp v22, v22, v22 row_mirror row_mask:0xf bank_mask:0xf bound_ctrl:1
	s_nop 0
	v_readlane_b32 s12, v22, 16
	v_readlane_b32 s13, v22, 48
	v_readlane_b32 s10, v22, 0
	v_readlane_b32 s11, v22, 32
	v_mov_b32_e32 v22, s12
	v_mov_b32_e32 v23, s13
	v_pk_add_f32 v[22:23], s[10:11], v[22:23]
	s_nop 0
	v_add_f32_e32 v22, v22, v23
	v_fmamk_f32 v22, v22, 0x3b800000, v3
	v_mul_f32_e32 v23, 0x4b800000, v22
	v_cmp_gt_f32_e32 vcc, s8, v22
	s_nop 1
	v_cndmask_b32_e32 v22, v22, v23, vcc
	v_rsq_f32_e32 v22, v22
	s_nop 0
	v_mul_f32_e32 v23, 0x45800000, v22
	v_cndmask_b32_e32 v22, v22, v23, vcc
	v_pk_mul_f32 v[28:29], v[22:23], v[28:29] op_sel_hi:[0,1]
	v_pk_mul_f32 v[22:23], v[22:23], v[26:27] op_sel_hi:[0,1]
	v_pk_mul_f32 v[18:19], v[68:69], v[28:29]
	v_pk_mul_f32 v[20:21], v[70:71], v[22:23]
	v_cvt_pk_bf16_f32 v18, v18, v19
	v_cvt_pk_bf16_f32 v19, v20, v21
	global_store_dwordx2 v[24:25], v[18:19], off
	s_ashr_i32 s11, s9, 9
	s_and_b32 s11, s11, 0x7fffffc
	s_bfe_u32 s10, s9, 0x50006
	v_or_b32_e32 v24, s11, v1
	v_lshl_or_b32 v24, v24, 5, s10
	v_ashrrev_i32_e32 v25, 31, v24
	s_lshr_b32 s12, s9, 2
	v_lshlrev_b64 v[24:25], 4, v[24:25]
	v_and_or_b32 v24, s12, 12, v24
	v_or_b32_e32 v24, v24, v0
	v_lshlrev_b64 v[24:25], 6, v[24:25]
	v_or_b32_e32 v24, v24, v2
	v_and_or_b32 v24, s9, 15, v24
	v_lshl_add_u64 v[24:25], v[24:25], 4, s[40:41]
	v_lshl_add_u64 v[30:31], s[86:87], 0, v[10:11]
	s_add_i32 s9, s9, s96
	v_lshl_add_u64 v[10:11], v[10:11], 0, s[2:3]
	s_waitcnt vmcnt(23)
	global_store_dwordx4 v[24:25], v[148:151], off
	s_waitcnt vmcnt(23)
	v_lshlrev_b32_e32 v38, 16, v152
	v_and_b32_e32 v39, 0xffff0000, v152
	v_lshlrev_b32_e32 v34, 16, v155
	v_and_b32_e32 v35, 0xffff0000, v155
	v_lshlrev_b32_e32 v36, 16, v154
	v_and_b32_e32 v37, 0xffff0000, v154
	v_lshlrev_b32_e32 v20, 16, v153
	v_and_b32_e32 v21, 0xffff0000, v153
	v_pk_mul_f32 v[44:45], v[38:39], v[38:39]
	v_pk_mul_f32 v[42:43], v[20:21], v[20:21]
	v_add_f32_e32 v44, v44, v45
	v_add_f32_e32 v42, v44, v42
	v_pk_mul_f32 v[40:41], v[36:37], v[36:37]
	v_add_f32_e32 v42, v42, v43
	v_add_f32_e32 v40, v42, v40
	v_pk_mul_f32 v[18:19], v[34:35], v[34:35]
	v_add_f32_e32 v40, v40, v41
	v_add_f32_e32 v18, v40, v18
	v_add_f32_e32 v18, v18, v19
	s_nop 1
	v_add_f32_dpp v18, v18, v18 quad_perm:[1,0,3,2] row_mask:0xf bank_mask:0xf bound_ctrl:1
	s_nop 1
	v_add_f32_dpp v18, v18, v18 quad_perm:[2,3,0,1] row_mask:0xf bank_mask:0xf bound_ctrl:1
	s_nop 1
	v_add_f32_dpp v18, v18, v18 row_half_mirror row_mask:0xf bank_mask:0xf bound_ctrl:1
	s_nop 1
	v_add_f32_dpp v18, v18, v18 row_mirror row_mask:0xf bank_mask:0xf bound_ctrl:1
	s_nop 0
	v_readlane_b32 s12, v18, 16
	v_readlane_b32 s13, v18, 48
	v_readlane_b32 s10, v18, 0
	v_readlane_b32 s11, v18, 32
	v_mov_b32_e32 v18, s12
	v_mov_b32_e32 v19, s13
	v_pk_add_f32 v[18:19], s[10:11], v[18:19]
	s_nop 0
	v_add_f32_e32 v18, v18, v19
	v_fmamk_f32 v18, v18, 0x3b000000, v3
	v_mul_f32_e32 v19, 0x4b800000, v18
	v_cmp_gt_f32_e32 vcc, s8, v18
	s_nop 1
	v_cndmask_b32_e32 v18, v18, v19, vcc
	v_rsq_f32_e32 v18, v18
	s_nop 0
	v_mul_f32_e32 v19, 0x45800000, v18
	v_cndmask_b32_e32 v18, v18, v19, vcc
	v_pk_mul_f32 v[38:39], v[18:19], v[38:39] op_sel_hi:[0,1]
	v_pk_mul_f32 v[20:21], v[18:19], v[20:21] op_sel_hi:[0,1]
	v_pk_mul_f32 v[36:37], v[18:19], v[36:37] op_sel_hi:[0,1]
	v_pk_mul_f32 v[18:19], v[18:19], v[34:35] op_sel_hi:[0,1]
	v_pk_mul_f32 v[22:23], v[60:61], v[38:39]
	v_pk_mul_f32 v[20:21], v[62:63], v[20:21]
	v_pk_mul_f32 v[24:25], v[64:65], v[36:37]
	v_pk_mul_f32 v[26:27], v[66:67], v[18:19]
	v_cvt_pk_bf16_f32 v18, v22, v23
	v_cvt_pk_bf16_f32 v19, v20, v21
	v_cvt_pk_bf16_f32 v20, v24, v25
	v_cvt_pk_bf16_f32 v21, v26, v27
	global_store_dwordx4 v[30:31], v[18:21], off
	v_lshl_add_u64 v[24:25], s[86:87], 0, v[8:9]
	v_lshl_add_u64 v[8:9], v[8:9], 0, s[0:1]
	s_waitcnt vmcnt(23)
	v_lshlrev_b32_e32 v28, 16, v156
	v_and_b32_e32 v29, 0xffff0000, v156
	v_lshlrev_b32_e32 v26, 16, v157
	v_and_b32_e32 v27, 0xffff0000, v157
	v_pk_mul_f32 v[30:31], v[28:29], v[28:29]
	v_pk_mul_f32 v[22:23], v[26:27], v[26:27]
	v_add_f32_e32 v30, v30, v31
	v_add_f32_e32 v22, v22, v30
	v_add_f32_e32 v22, v23, v22
	s_nop 1
	v_add_f32_dpp v22, v22, v22 quad_perm:[1,0,3,2] row_mask:0xf bank_mask:0xf bound_ctrl:1
	s_nop 1
	v_add_f32_dpp v22, v22, v22 quad_perm:[2,3,0,1] row_mask:0xf bank_mask:0xf bound_ctrl:1
	s_nop 1
	v_add_f32_dpp v22, v22, v22 row_half_mirror row_mask:0xf bank_mask:0xf bound_ctrl:1
	s_nop 1
	v_add_f32_dpp v22, v22, v22 row_mirror row_mask:0xf bank_mask:0xf bound_ctrl:1
	s_nop 0
	v_readlane_b32 s12, v22, 16
	v_readlane_b32 s13, v22, 48
	v_readlane_b32 s10, v22, 0
	v_readlane_b32 s11, v22, 32
	v_mov_b32_e32 v22, s12
	v_mov_b32_e32 v23, s13
	v_pk_add_f32 v[22:23], s[10:11], v[22:23]
	s_nop 0
	v_add_f32_e32 v22, v22, v23
	v_fmamk_f32 v22, v22, 0x3b800000, v3
	v_mul_f32_e32 v23, 0x4b800000, v22
	v_cmp_gt_f32_e32 vcc, s8, v22
	s_nop 1
	v_cndmask_b32_e32 v22, v22, v23, vcc
	v_rsq_f32_e32 v22, v22
	s_nop 0
	v_mul_f32_e32 v23, 0x45800000, v22
	v_cndmask_b32_e32 v22, v22, v23, vcc
	v_pk_mul_f32 v[28:29], v[22:23], v[28:29] op_sel_hi:[0,1]
	v_pk_mul_f32 v[22:23], v[22:23], v[26:27] op_sel_hi:[0,1]
	v_pk_mul_f32 v[18:19], v[68:69], v[28:29]
	v_pk_mul_f32 v[20:21], v[70:71], v[22:23]
	v_cvt_pk_bf16_f32 v18, v18, v19
	v_cvt_pk_bf16_f32 v19, v20, v21
	global_store_dwordx2 v[24:25], v[18:19], off
	s_ashr_i32 s11, s9, 9
	s_and_b32 s11, s11, 0x7fffffc
	s_bfe_u32 s10, s9, 0x50006
	v_or_b32_e32 v24, s11, v1
	v_lshl_or_b32 v24, v24, 5, s10
	v_ashrrev_i32_e32 v25, 31, v24
	s_lshr_b32 s12, s9, 2
	v_lshlrev_b64 v[24:25], 4, v[24:25]
	v_and_or_b32 v24, s12, 12, v24
	v_or_b32_e32 v24, v24, v0
	v_lshlrev_b64 v[24:25], 6, v[24:25]
	v_or_b32_e32 v24, v24, v2
	v_and_or_b32 v24, s9, 15, v24
	v_lshl_add_u64 v[24:25], v[24:25], 4, s[40:41]
	v_lshl_add_u64 v[30:31], s[86:87], 0, v[10:11]
	s_add_i32 s9, s9, s96
	v_lshl_add_u64 v[10:11], v[10:11], 0, s[2:3]
	s_waitcnt vmcnt(23)
; __device__ __forceinline__ unsigned pk2(float lo, float hi) { f32x2_t v = {lo, hi}; bf16x2_t b = __builtin_convertvector(v, bf16x2_t); return __builtin_bit_cast(unsigned, b); }
; __global__ void __launch_bounds__(512, 2) mega_fwd(Args args) {
;     ...
;                 const int h_ = lane >> 4, pc = lane & 15, fr_ = m & 15, fw_ = (m >> 4) & 3, ch_ = (m >> 6) & 31, b_ = m >> 11;
;                 const u32x4 gqv = *(const u32x4*)(zr + ZGQ + h_ * 128 + pc * 8);
;                 *(u32x4*)(H + ((((size_t)((b_ * 4 + h_) * 32 + ch_) * 4 + fw_) * 4 + (pc >> 2)) * 64 + (pc & 3) * 16 + fr_) * 8) = gqv;
;             }
;             {
;                 const u32x4 u = *(const u32x4*)(zr + ZQ + lane * 8);
;                 float v[8] = {bflo(u.x), bfhi(u.x), bflo(u.y), bfhi(u.y), bflo(u.z), bfhi(u.z), bflo(u.w), bfhi(u.w)};
;                 float sq = 0.f;
; #pragma unroll
;                 for (int e = 0; e < 8; ++e) sq += v[e] * v[e];
;                 const float r = rsqrtf(wave_sum(sq) * (1.f / 512.f) + EPS);
;                 const f32x4 g0 = *(const f32x4*)(args.in[9] + lane * 8), g1 = *(const f32x4*)(args.in[9] + lane * 8 + 4);
;                 u32x4 w; w.x = pk2(v[0] * r * g0.x, v[1] * r * g0.y); w.y = pk2(v[2] * r * g0.z, v[3] * r * g0.w); w.z = pk2(v[4] * r * g1.x, v[5] * r * g1.y); w.w = pk2(v[6] * r * g1.z, v[7] * r * g1.w);
;                 *(u32x4*)(QA + (size_t)m * 512 + lane * 8) = w;
;             }
;             {
;                 const u32x2 u = *(const u32x2*)(zr + ZKV + lane * 4);
;                 const float v0 = bflo(u.x), v1 = bfhi(u.x), v2 = bflo(u.y), v3 = bfhi(u.y);
;                 const float r = rsqrtf(wave_sum(v0 * v0 + v1 * v1 + v2 * v2 + v3 * v3) * (1.f / 256.f) + EPS);
;                 const f32x4 g0 = *(const f32x4*)(args.in[11] + lane * 4);
;                 u32x2 w; w.x = pk2(v0 * r * g0.x, v1 * r * g0.y); w.y = pk2(v2 * r * g0.z, v3 * r * g0.w);
;                 *(u32x2*)(KVA + (size_t)m * 256 + lane * 4) = w;
;             }
	global_store_dwordx4 v[24:25], v[166:169], off
	s_waitcnt vmcnt(23)
	v_lshlrev_b32_e32 v38, 16, v170
	v_and_b32_e32 v39, 0xffff0000, v170
	v_lshlrev_b32_e32 v34, 16, v173
	v_and_b32_e32 v35, 0xffff0000, v173
	v_lshlrev_b32_e32 v36, 16, v172
	v_and_b32_e32 v37, 0xffff0000, v172
	v_lshlrev_b32_e32 v20, 16, v171
	v_and_b32_e32 v21, 0xffff0000, v171
	v_pk_mul_f32 v[44:45], v[38:39], v[38:39]
	v_pk_mul_f32 v[42:43], v[20:21], v[20:21]
	v_add_f32_e32 v44, v44, v45
	v_add_f32_e32 v42, v44, v42
	v_pk_mul_f32 v[40:41], v[36:37], v[36:37]
	v_add_f32_e32 v42, v42, v43
	v_add_f32_e32 v40, v42, v40
	v_pk_mul_f32 v[18:19], v[34:35], v[34:35]
	v_add_f32_e32 v40, v40, v41
	v_add_f32_e32 v18, v40, v18
	v_add_f32_e32 v18, v18, v19
	s_nop 1
	v_add_f32_dpp v18, v18, v18 quad_perm:[1,0,3,2] row_mask:0xf bank_mask:0xf bound_ctrl:1
	s_nop 1
	v_add_f32_dpp v18, v18, v18 quad_perm:[2,3,0,1] row_mask:0xf bank_mask:0xf bound_ctrl:1
	s_nop 1
	v_add_f32_dpp v18, v18, v18 row_half_mirror row_mask:0xf bank_mask:0xf bound_ctrl:1
	s_nop 1
	v_add_f32_dpp v18, v18, v18 row_mirror row_mask:0xf bank_mask:0xf bound_ctrl:1
	s_nop 0
	v_readlane_b32 s12, v18, 16
	v_readlane_b32 s13, v18, 48
	v_readlane_b32 s10, v18, 0
	v_readlane_b32 s11, v18, 32
	v_mov_b32_e32 v18, s12
	v_mov_b32_e32 v19, s13
	v_pk_add_f32 v[18:19], s[10:11], v[18:19]
	s_nop 0
	v_add_f32_e32 v18, v18, v19
	v_fmamk_f32 v18, v18, 0x3b000000, v3
	v_mul_f32_e32 v19, 0x4b800000, v18
	v_cmp_gt_f32_e32 vcc, s8, v18
	s_nop 1
	v_cndmask_b32_e32 v18, v18, v19, vcc
	v_rsq_f32_e32 v18, v18
	s_nop 0
	v_mul_f32_e32 v19, 0x45800000, v18
	v_cndmask_b32_e32 v18, v18, v19, vcc
	v_pk_mul_f32 v[38:39], v[18:19], v[38:39] op_sel_hi:[0,1]
	v_pk_mul_f32 v[20:21], v[18:19], v[20:21] op_sel_hi:[0,1]
	v_pk_mul_f32 v[36:37], v[18:19], v[36:37] op_sel_hi:[0,1]
	v_pk_mul_f32 v[18:19], v[18:19], v[34:35] op_sel_hi:[0,1]
	v_pk_mul_f32 v[22:23], v[60:61], v[38:39]
	v_pk_mul_f32 v[20:21], v[62:63], v[20:21]
	v_pk_mul_f32 v[24:25], v[64:65], v[36:37]
	v_pk_mul_f32 v[26:27], v[66:67], v[18:19]
	v_cvt_pk_bf16_f32 v18, v22, v23
	v_cvt_pk_bf16_f32 v19, v20, v21
	v_cvt_pk_bf16_f32 v20, v24, v25
	v_cvt_pk_bf16_f32 v21, v26, v27
	global_store_dwordx4 v[30:31], v[18:21], off
	v_lshl_add_u64 v[24:25], s[86:87], 0, v[8:9]
	v_lshl_add_u64 v[8:9], v[8:9], 0, s[0:1]
	s_waitcnt vmcnt(23)
	v_lshlrev_b32_e32 v28, 16, v174
	v_and_b32_e32 v29, 0xffff0000, v174
	v_lshlrev_b32_e32 v26, 16, v175
	v_and_b32_e32 v27, 0xffff0000, v175
	v_pk_mul_f32 v[30:31], v[28:29], v[28:29]
	v_pk_mul_f32 v[22:23], v[26:27], v[26:27]
	v_add_f32_e32 v30, v30, v31
	v_add_f32_e32 v22, v22, v30
	v_add_f32_e32 v22, v23, v22
	s_nop 1
	v_add_f32_dpp v22, v22, v22 quad_perm:[1,0,3,2] row_mask:0xf bank_mask:0xf bound_ctrl:1
	s_nop 1
	v_add_f32_dpp v22, v22, v22 quad_perm:[2,3,0,1] row_mask:0xf bank_mask:0xf bound_ctrl:1
	s_nop 1
	v_add_f32_dpp v22, v22, v22 row_half_mirror row_mask:0xf bank_mask:0xf bound_ctrl:1
	s_nop 1
	v_add_f32_dpp v22, v22, v22 row_mirror row_mask:0xf bank_mask:0xf bound_ctrl:1
	s_nop 0
	v_readlane_b32 s12, v22, 16
	v_readlane_b32 s13, v22, 48
	v_readlane_b32 s10, v22, 0
	v_readlane_b32 s11, v22, 32
	v_mov_b32_e32 v22, s12
	v_mov_b32_e32 v23, s13
	v_pk_add_f32 v[22:23], s[10:11], v[22:23]
	s_nop 0
	v_add_f32_e32 v22, v22, v23
	v_fmamk_f32 v22, v22, 0x3b800000, v3
	v_mul_f32_e32 v23, 0x4b800000, v22
	v_cmp_gt_f32_e32 vcc, s8, v22
	s_nop 1
	v_cndmask_b32_e32 v22, v22, v23, vcc
	v_rsq_f32_e32 v22, v22
	s_nop 0
	v_mul_f32_e32 v23, 0x45800000, v22
	v_cndmask_b32_e32 v22, v22, v23, vcc
	v_pk_mul_f32 v[28:29], v[22:23], v[28:29] op_sel_hi:[0,1]
	v_pk_mul_f32 v[22:23], v[22:23], v[26:27] op_sel_hi:[0,1]
	v_pk_mul_f32 v[18:19], v[68:69], v[28:29]
	v_pk_mul_f32 v[20:21], v[70:71], v[22:23]
	v_cvt_pk_bf16_f32 v18, v18, v19
	v_cvt_pk_bf16_f32 v19, v20, v21
	global_store_dwordx2 v[24:25], v[18:19], off
	s_ashr_i32 s11, s9, 9
	s_and_b32 s11, s11, 0x7fffffc
	s_bfe_u32 s10, s9, 0x50006
	v_or_b32_e32 v24, s11, v1
	v_lshl_or_b32 v24, v24, 5, s10
	v_ashrrev_i32_e32 v25, 31, v24
	s_lshr_b32 s12, s9, 2
	v_lshlrev_b64 v[24:25], 4, v[24:25]
	v_and_or_b32 v24, s12, 12, v24
	v_or_b32_e32 v24, v24, v0
	v_lshlrev_b64 v[24:25], 6, v[24:25]
	v_or_b32_e32 v24, v24, v2
	v_and_or_b32 v24, s9, 15, v24
	v_lshl_add_u64 v[24:25], v[24:25], 4, s[40:41]
	v_lshl_add_u64 v[30:31], s[86:87], 0, v[10:11]
	s_add_i32 s9, s9, s96
	v_lshl_add_u64 v[10:11], v[10:11], 0, s[2:3]
	s_waitcnt vmcnt(23)
; __device__ __forceinline__ unsigned pk2(float lo, float hi) { f32x2_t v = {lo, hi}; bf16x2_t b = __builtin_convertvector(v, bf16x2_t); return __builtin_bit_cast(unsigned, b); }
; __global__ void __launch_bounds__(512, 2) mega_fwd(Args args) {
;     ...
;                 const int h_ = lane >> 4, pc = lane & 15, fr_ = m & 15, fw_ = (m >> 4) & 3, ch_ = (m >> 6) & 31, b_ = m >> 11;
;                 const u32x4 gqv = *(const u32x4*)(zr + ZGQ + h_ * 128 + pc * 8);
;                 *(u32x4*)(H + ((((size_t)((b_ * 4 + h_) * 32 + ch_) * 4 + fw_) * 4 + (pc >> 2)) * 64 + (pc & 3) * 16 + fr_) * 8) = gqv;
;             }
;             {
;                 const u32x4 u = *(const u32x4*)(zr + ZQ + lane * 8);
;                 float v[8] = {bflo(u.x), bfhi(u.x), bflo(u.y), bfhi(u.y), bflo(u.z), bfhi(u.z), bflo(u.w), bfhi(u.w)};
;                 float sq = 0.f;
; #pragma unroll
;                 for (int e = 0; e < 8; ++e) sq += v[e] * v[e];
;                 const float r = rsqrtf(wave_sum(sq) * (1.f / 512.f) + EPS);
;                 const f32x4 g0 = *(const f32x4*)(args.in[9] + lane * 8), g1 = *(const f32x4*)(args.in[9] + lane * 8 + 4);
;                 u32x4 w; w.x = pk2(v[0] * r * g0.x, v[1] * r * g0.y); w.y = pk2(v[2] * r * g0.z, v[3] * r * g0.w); w.z = pk2(v[4] * r * g1.x, v[5] * r * g1.y); w.w = pk2(v[6] * r * g1.z, v[7] * r * g1.w);
;                 *(u32x4*)(QA + (size_t)m * 512 + lane * 8) = w;
;             }
;             {
;                 const u32x2 u = *(const u32x2*)(zr + ZKV + lane * 4);
;                 const float v0 = bflo(u.x), v1 = bfhi(u.x), v2 = bflo(u.y), v3 = bfhi(u.y);
;                 const float r = rsqrtf(wave_sum(v0 * v0 + v1 * v1 + v2 * v2 + v3 * v3) * (1.f / 256.f) + EPS);
;                 const f32x4 g0 = *(const f32x4*)(args.in[11] + lane * 4);
;                 u32x2 w; w.x = pk2(v0 * r * g0.x, v1 * r * g0.y); w.y = pk2(v2 * r * g0.z, v3 * r * g0.w);
;                 *(u32x2*)(KVA + (size_t)m * 256 + lane * 4) = w;
;             }
	global_store_dwordx4 v[24:25], v[140:143], off
	s_waitcnt vmcnt(23)
	v_lshlrev_b32_e32 v38, 16, v158
	v_and_b32_e32 v39, 0xffff0000, v158
	v_lshlrev_b32_e32 v34, 16, v161
	v_and_b32_e32 v35, 0xffff0000, v161
	v_lshlrev_b32_e32 v36, 16, v160
	v_and_b32_e32 v37, 0xffff0000, v160
	v_lshlrev_b32_e32 v20, 16, v159
	v_and_b32_e32 v21, 0xffff0000, v159
	v_pk_mul_f32 v[44:45], v[38:39], v[38:39]
	v_pk_mul_f32 v[42:43], v[20:21], v[20:21]
	v_add_f32_e32 v44, v44, v45
	v_add_f32_e32 v42, v44, v42
	v_pk_mul_f32 v[40:41], v[36:37], v[36:37]
	v_add_f32_e32 v42, v42, v43
	v_add_f32_e32 v40, v42, v40
	v_pk_mul_f32 v[18:19], v[34:35], v[34:35]
	v_add_f32_e32 v40, v40, v41
	v_add_f32_e32 v18, v40, v18
	v_add_f32_e32 v18, v18, v19
	s_nop 1
	v_add_f32_dpp v18, v18, v18 quad_perm:[1,0,3,2] row_mask:0xf bank_mask:0xf bound_ctrl:1
	s_nop 1
	v_add_f32_dpp v18, v18, v18 quad_perm:[2,3,0,1] row_mask:0xf bank_mask:0xf bound_ctrl:1
	s_nop 1
	v_add_f32_dpp v18, v18, v18 row_half_mirror row_mask:0xf bank_mask:0xf bound_ctrl:1
	s_nop 1
	v_add_f32_dpp v18, v18, v18 row_mirror row_mask:0xf bank_mask:0xf bound_ctrl:1
	s_nop 0
	v_readlane_b32 s12, v18, 16
	v_readlane_b32 s13, v18, 48
	v_readlane_b32 s10, v18, 0
	v_readlane_b32 s11, v18, 32
	v_mov_b32_e32 v18, s12
	v_mov_b32_e32 v19, s13
	v_pk_add_f32 v[18:19], s[10:11], v[18:19]
	s_nop 0
	v_add_f32_e32 v18, v18, v19
	v_fmamk_f32 v18, v18, 0x3b000000, v3
	v_mul_f32_e32 v19, 0x4b800000, v18
	v_cmp_gt_f32_e32 vcc, s8, v18
	s_nop 1
	v_cndmask_b32_e32 v18, v18, v19, vcc
	v_rsq_f32_e32 v18, v18
	s_nop 0
	v_mul_f32_e32 v19, 0x45800000, v18
	v_cndmask_b32_e32 v18, v18, v19, vcc
	v_pk_mul_f32 v[38:39], v[18:19], v[38:39] op_sel_hi:[0,1]
	v_pk_mul_f32 v[20:21], v[18:19], v[20:21] op_sel_hi:[0,1]
	v_pk_mul_f32 v[36:37], v[18:19], v[36:37] op_sel_hi:[0,1]
	v_pk_mul_f32 v[18:19], v[18:19], v[34:35] op_sel_hi:[0,1]
	v_pk_mul_f32 v[22:23], v[60:61], v[38:39]
	v_pk_mul_f32 v[20:21], v[62:63], v[20:21]
	v_pk_mul_f32 v[24:25], v[64:65], v[36:37]
	v_pk_mul_f32 v[26:27], v[66:67], v[18:19]
	v_cvt_pk_bf16_f32 v18, v22, v23
	v_cvt_pk_bf16_f32 v19, v20, v21
	v_cvt_pk_bf16_f32 v20, v24, v25
	v_cvt_pk_bf16_f32 v21, v26, v27
	global_store_dwordx4 v[30:31], v[18:21], off
	v_lshl_add_u64 v[24:25], s[86:87], 0, v[8:9]
	v_lshl_add_u64 v[8:9], v[8:9], 0, s[0:1]
	s_waitcnt vmcnt(23)
	v_lshlrev_b32_e32 v28, 16, v162
	v_and_b32_e32 v29, 0xffff0000, v162
	v_lshlrev_b32_e32 v26, 16, v163
	v_and_b32_e32 v27, 0xffff0000, v163
	v_pk_mul_f32 v[30:31], v[28:29], v[28:29]
	v_pk_mul_f32 v[22:23], v[26:27], v[26:27]
	v_add_f32_e32 v30, v30, v31
	v_add_f32_e32 v22, v22, v30
	v_add_f32_e32 v22, v23, v22
	s_nop 1
	v_add_f32_dpp v22, v22, v22 quad_perm:[1,0,3,2] row_mask:0xf bank_mask:0xf bound_ctrl:1
	s_nop 1
	v_add_f32_dpp v22, v22, v22 quad_perm:[2,3,0,1] row_mask:0xf bank_mask:0xf bound_ctrl:1
	s_nop 1
	v_add_f32_dpp v22, v22, v22 row_half_mirror row_mask:0xf bank_mask:0xf bound_ctrl:1
	s_nop 1
	v_add_f32_dpp v22, v22, v22 row_mirror row_mask:0xf bank_mask:0xf bound_ctrl:1
	s_nop 0
	v_readlane_b32 s12, v22, 16
	v_readlane_b32 s13, v22, 48
	v_readlane_b32 s10, v22, 0
	v_readlane_b32 s11, v22, 32
	v_mov_b32_e32 v22, s12
	v_mov_b32_e32 v23, s13
	v_pk_add_f32 v[22:23], s[10:11], v[22:23]
	s_nop 0
	v_add_f32_e32 v22, v22, v23
	v_fmamk_f32 v22, v22, 0x3b800000, v3
	v_mul_f32_e32 v23, 0x4b800000, v22
	v_cmp_gt_f32_e32 vcc, s8, v22
	s_nop 1
	v_cndmask_b32_e32 v22, v22, v23, vcc
	v_rsq_f32_e32 v22, v22
	s_nop 0
	v_mul_f32_e32 v23, 0x45800000, v22
	v_cndmask_b32_e32 v22, v22, v23, vcc
	v_pk_mul_f32 v[28:29], v[22:23], v[28:29] op_sel_hi:[0,1]
	v_pk_mul_f32 v[22:23], v[22:23], v[26:27] op_sel_hi:[0,1]
	v_pk_mul_f32 v[18:19], v[68:69], v[28:29]
	v_pk_mul_f32 v[20:21], v[70:71], v[22:23]
	v_cvt_pk_bf16_f32 v18, v18, v19
	v_cvt_pk_bf16_f32 v19, v20, v21
	global_store_dwordx2 v[24:25], v[18:19], off
	s_branch .LBB0_603
